# attention: running max refreshed only when it grows by more than 4 log2 units (exact rescale math kept)
# speedup vs baseline: 1.0304x; 1.0201x over previous
; __device__ __forceinline__ void attn_phase(LAS unsigned char* ldsb, bf16_t* P, const bf16_t* Kn, const bf16_t* KPE, const bf16_t* VT) {
;     ...
;                     float mx = st[0][0];
; #pragma unroll
;                     for (int kb = 0; kb < 2; ++kb)
; #pragma unroll
;                         for (int i = 0; i < 16; ++i) mx = fmaxf(mx, st[kb][i]);
;                     mx = fmaxf(mx, __shfl_xor(mx, 32));
;                     if (__builtin_amdgcn_ballot_w64(mx > mrun) != 0ull) {
;                         const float mnew = fmaxf(mrun, mx);
;                         const float alpha = __builtin_amdgcn_exp2f(mrun - mnew);
;                         mrun = mnew; lrun *= alpha;
; #pragma unroll
;                         for (int d = 0; d < 4; ++d)
; #pragma unroll
;                             for (int i = 0; i < 16; ++i) o[d][i] *= alpha;
;                     }
.LBB0_1530:
	s_nop 9
	v_max_f32_e32 v0, v97, v97
	v_max_f32_e32 v2, v96, v96
	v_max_f32_e32 v0, v2, v0
	v_max3_f32 v0, v0, v98, v99
	v_max3_f32 v0, v0, v100, v101
	v_max3_f32 v0, v0, v102, v103
	v_max3_f32 v0, v0, v104, v105
	v_max3_f32 v0, v0, v106, v107
	v_max3_f32 v0, v0, v108, v109
	v_max3_f32 v0, v0, v110, v111
	v_max3_f32 v0, v0, v80, v81
	v_max3_f32 v0, v0, v82, v83
	v_max3_f32 v0, v0, v84, v85
	v_max3_f32 v0, v0, v86, v87
	v_and_b32_e32 v3, 64, v234
	v_max3_f32 v0, v0, v88, v89
	v_xor_b32_e32 v2, 32, v234
	v_add_u32_e32 v3, 64, v3
	v_max3_f32 v0, v0, v90, v91
	v_cmp_lt_i32_e32 vcc, v2, v3
	v_max3_f32 v0, v0, v92, v93
	v_max3_f32 v0, v0, v94, v95
	v_cndmask_b32_e32 v2, v234, v2, vcc
	v_lshlrev_b32_e32 v2, 2, v2
	ds_bpermute_b32 v2, v2, v0
	s_waitcnt lgkmcnt(0)
	v_max_f32_e32 v2, v2, v2
	v_max_f32_e32 v0, v0, v2
	v_sub_f32_e32 v2, v0, v240
	v_cmp_lt_f32_e32 vcc, 4.0, v2
	s_cbranch_vccz .LBB0_1525
	v_max_f32_e32 v0, v0, v0
	v_max_f32_e32 v2, v240, v240
	v_max_f32_e32 v2, v2, v0
	v_sub_f32_e32 v0, v240, v2
	v_exp_f32_e32 v0, v0
	v_mov_b32_e32 v240, v2
	v_pk_mul_f32 v[78:79], v[78:79], v[0:1] op_sel_hi:[1,0]
	v_pk_mul_f32 v[76:77], v[76:77], v[0:1] op_sel_hi:[1,0]
	v_pk_mul_f32 v[74:75], v[74:75], v[0:1] op_sel_hi:[1,0]
	v_pk_mul_f32 v[72:73], v[72:73], v[0:1] op_sel_hi:[1,0]
	v_pk_mul_f32 v[70:71], v[70:71], v[0:1] op_sel_hi:[1,0]
	v_pk_mul_f32 v[68:69], v[68:69], v[0:1] op_sel_hi:[1,0]
	v_pk_mul_f32 v[66:67], v[66:67], v[0:1] op_sel_hi:[1,0]
	v_pk_mul_f32 v[64:65], v[64:65], v[0:1] op_sel_hi:[1,0]
	v_pk_mul_f32 v[62:63], v[62:63], v[0:1] op_sel_hi:[1,0]
	v_pk_mul_f32 v[60:61], v[60:61], v[0:1] op_sel_hi:[1,0]
	v_pk_mul_f32 v[58:59], v[58:59], v[0:1] op_sel_hi:[1,0]
	v_pk_mul_f32 v[56:57], v[56:57], v[0:1] op_sel_hi:[1,0]
	v_pk_mul_f32 v[54:55], v[54:55], v[0:1] op_sel_hi:[1,0]
	v_pk_mul_f32 v[52:53], v[52:53], v[0:1] op_sel_hi:[1,0]
	v_pk_mul_f32 v[50:51], v[50:51], v[0:1] op_sel_hi:[1,0]
	v_pk_mul_f32 v[48:49], v[48:49], v[0:1] op_sel_hi:[1,0]
	v_pk_mul_f32 v[46:47], v[46:47], v[0:1] op_sel_hi:[1,0]
	v_pk_mul_f32 v[44:45], v[44:45], v[0:1] op_sel_hi:[1,0]
	v_pk_mul_f32 v[42:43], v[42:43], v[0:1] op_sel_hi:[1,0]
	v_pk_mul_f32 v[40:41], v[40:41], v[0:1] op_sel_hi:[1,0]
	v_pk_mul_f32 v[38:39], v[38:39], v[0:1] op_sel_hi:[1,0]
	v_pk_mul_f32 v[36:37], v[36:37], v[0:1] op_sel_hi:[1,0]
	v_pk_mul_f32 v[34:35], v[34:35], v[0:1] op_sel_hi:[1,0]
	v_pk_mul_f32 v[32:33], v[32:33], v[0:1] op_sel_hi:[1,0]
	v_pk_mul_f32 v[30:31], v[30:31], v[0:1] op_sel_hi:[1,0]
	v_pk_mul_f32 v[28:29], v[28:29], v[0:1] op_sel_hi:[1,0]
	v_pk_mul_f32 v[26:27], v[26:27], v[0:1] op_sel_hi:[1,0]
	v_pk_mul_f32 v[24:25], v[24:25], v[0:1] op_sel_hi:[1,0]
	v_pk_mul_f32 v[22:23], v[22:23], v[0:1] op_sel_hi:[1,0]
	v_pk_mul_f32 v[20:21], v[20:21], v[0:1] op_sel_hi:[1,0]
	v_pk_mul_f32 v[18:19], v[18:19], v[0:1] op_sel_hi:[1,0]
	v_pk_mul_f32 v[16:17], v[16:17], v[0:1] op_sel_hi:[1,0]
	v_mul_f32_e32 v236, v236, v0
	s_branch .LBB0_1525
